# PD: drop item-start store drains; preload ml head-norm weights ahead of epilogue
# baseline (speedup 1.0000x reference)
.LBB0_197:
	s_or_b64 exec, exec, s[0:1]
	s_add_i32 s0, 16, 0x23a00
	s_waitcnt vmcnt(15)
	v_lshl_add_u32 v10, v95, 4, s0
	s_waitcnt lgkmcnt(0)
	s_barrier
	ds_read_b32 v11, v10
	v_lshlrev_b32_e32 v8, 2, v96
	s_waitcnt vmcnt(14)
	v_mul_u32_u24_e32 v13, 0x410, v95
	v_add_u32_e32 v9, 16, v8
	v_add_lshl_u32 v13, v13, s17, 2
	s_waitcnt lgkmcnt(0)
	v_mul_f32_e32 v12, v24, v11
	v_add_u32_e32 v14, v9, v13
	ds_write_b32 v14, v12 offset:17408
	v_mul_f32_e32 v11, v28, v11
	v_add3_u32 v12, 16, v13, v8
	ds_write_b32 v12, v11 offset:17472
	v_lshl_or_b32 v11, v95, 2, 1
	v_lshl_add_u32 v12, v11, 2, s0
	ds_read_b32 v12, v12
	v_mul_u32_u24_e32 v11, 0x104, v11
	v_add_lshl_u32 v11, v11, s17, 2
	v_add_u32_e32 v9, v9, v11
	v_add3_u32 v8, 16, v11, v8
	s_waitcnt lgkmcnt(0)
	v_mul_f32_e32 v13, v25, v12
	ds_write_b32 v9, v13 offset:17408
	v_mul_f32_e32 v9, v29, v12
	ds_write_b32 v8, v9 offset:17472
	ds_read_b32 v9, v10 offset:8
	v_add_u32_e32 v13, 0x4800, v8
	v_add_u32_e32 v14, 0x4c00, v8
	v_add_u32_e32 v15, 0x8000, v8
	v_add_u32_e32 v12, 0x410, v8
	s_waitcnt lgkmcnt(0)
	v_mul_f32_e32 v11, v26, v9
	v_mul_f32_e32 v9, v30, v9
	ds_write2_b32 v13, v11, v9 offset0:4 offset1:20
	ds_read_b32 v9, v10 offset:12
	v_add_u32_e32 v13, 0x820, v8
	s_movk_i32 s0, 0x410
	v_readlane_b32 s84, v254, 20
	v_readlane_b32 s86, v254, 22
	s_waitcnt lgkmcnt(0)
	v_mul_f32_e32 v11, v27, v9
	v_mul_f32_e32 v9, v31, v9
	ds_write2_b32 v14, v11, v9 offset0:8 offset1:24
	ds_read_b32 v9, v10 offset:64
	v_add_u32_e32 v14, 0x3cf0, v8
	v_readlane_b32 s87, v254, 23
	s_waitcnt vmcnt(11)
	v_lshlrev_b32_e32 v66, 16, v56
	v_and_b32_e32 v65, 0xffff0000, v56
	s_waitcnt lgkmcnt(0)
	v_mul_f32_e32 v11, v36, v9
	v_mul_f32_e32 v9, v48, v9
	ds_write2_b32 v15, v11, v9 offset0:60 offset1:76
	ds_read_b32 v9, v10 offset:68
	v_add_u32_e32 v15, 0x8400, v8
	v_lshlrev_b32_e32 v64, 16, v57
	v_and_b32_e32 v63, 0xffff0000, v57
	v_lshlrev_b32_e32 v57, 16, v58
	s_waitcnt lgkmcnt(0)
	v_mul_f32_e32 v11, v37, v9
	v_mul_f32_e32 v9, v49, v9
	ds_write2_b32 v15, v11, v9 offset0:64 offset1:80
	ds_read_b32 v9, v10 offset:72
	v_add_u32_e32 v15, 0x8800, v8
	v_and_b32_e32 v56, 0xffff0000, v58
	v_readlane_b32 s85, v254, 21
	v_readlane_b32 s88, v254, 24
	s_waitcnt lgkmcnt(0)
	v_mul_f32_e32 v11, v38, v9
	v_mul_f32_e32 v9, v50, v9
	ds_write2_b32 v15, v11, v9 offset0:68 offset1:84
	ds_read_b32 v9, v10 offset:76
	v_add_u32_e32 v15, 0x8c00, v8
	v_readlane_b32 s89, v254, 25
	v_readlane_b32 s90, v254, 26
	v_readlane_b32 s91, v254, 27
	s_waitcnt lgkmcnt(0)
	v_mul_f32_e32 v11, v39, v9
	v_mul_f32_e32 v9, v51, v9
	ds_write2_b32 v15, v11, v9 offset0:72 offset1:88
	ds_read_b32 v9, v10 offset:128
	v_add_u32_e32 v15, 0xc000, v8
	v_readlane_b32 s92, v254, 28
	v_readlane_b32 s93, v254, 29
	v_readlane_b32 s94, v254, 30
	s_waitcnt lgkmcnt(0)
	v_mul_f32_e32 v11, v32, v9
	v_mul_f32_e32 v9, v40, v9
	ds_write2_b32 v15, v11, v9 offset0:124 offset1:140
	ds_read_b32 v9, v10 offset:132
	v_add_u32_e32 v15, 0xc400, v8
	v_readlane_b32 s95, v254, 31
	v_readlane_b32 s96, v254, 32
	v_readlane_b32 s97, v254, 33
	s_waitcnt lgkmcnt(0)
	v_mul_f32_e32 v11, v33, v9
	v_mul_f32_e32 v9, v41, v9
	ds_write2_b32 v15, v11, v9 offset0:128 offset1:144
	ds_read_b32 v9, v10 offset:136
	v_add_u32_e32 v15, 0xc800, v8
	v_add_u32_e32 v8, 0xcc00, v8
	v_readlane_b32 s98, v254, 34
	v_readlane_b32 s99, v254, 35
	s_waitcnt lgkmcnt(0)
	v_mul_f32_e32 v11, v34, v9
	v_mul_f32_e32 v9, v42, v9
	ds_write2_b32 v15, v11, v9 offset0:132 offset1:148
	ds_read_b32 v9, v10 offset:140
	s_waitcnt lgkmcnt(0)
	v_mul_f32_e32 v11, v35, v9
	v_mul_f32_e32 v9, v43, v9
	ds_write2_b32 v8, v11, v9 offset0:136 offset1:152
	ds_read_b32 v8, v10 offset:192
	v_add_u32_e32 v11, 0xfc00, v12
	s_waitcnt lgkmcnt(0)
	v_mul_f32_e32 v9, v44, v8
	v_mul_f32_e32 v8, v52, v8
	ds_write2_b32 v11, v9, v8 offset0:184 offset1:200
	ds_read_b32 v8, v10 offset:196
	v_add_u32_e32 v11, 0xfc00, v13
	s_waitcnt lgkmcnt(0)
	v_mul_f32_e32 v9, v45, v8
	v_mul_f32_e32 v8, v53, v8
	ds_write2_b32 v11, v9, v8 offset0:184 offset1:200
	ds_read_b32 v8, v10 offset:200
	v_add_u32_e32 v11, 0xcc00, v14
	v_lshlrev_b32_e32 v53, 2, v62
	s_waitcnt lgkmcnt(0)
	v_mul_f32_e32 v9, v46, v8
	v_mul_f32_e32 v8, v54, v8
	ds_write2_b32 v11, v9, v8 offset0:136 offset1:152
	ds_read_b32 v8, v10 offset:204
	v_add_u32_e32 v10, 0xd000, v14
	v_and_b32_e32 v54, 0xffff0000, v59
	s_waitcnt lgkmcnt(0)
	v_mul_f32_e32 v9, v47, v8
	v_mul_f32_e32 v8, v55, v8
	ds_write2_b32 v10, v9, v8 offset0:140 offset1:156
	v_mul_lo_u32 v8, v94, s0
	v_lshlrev_b32_e32 v9, 2, v104
	v_add3_u32 v10, 16, v8, v9
	s_waitcnt lgkmcnt(0)
	s_barrier
	ds_read_b128 v[40:43], v10 offset:17408
	ds_read_b128 v[36:39], v10 offset:17424
	ds_read_b128 v[32:35], v10 offset:17664
	ds_read_b128 v[28:31], v10 offset:17680
	ds_read_b128 v[24:27], v10 offset:17920
	ds_read_b128 v[20:23], v10 offset:17936
	ds_read_b128 v[12:15], v10 offset:18176
	s_waitcnt lgkmcnt(6)
	v_mul_f32_e32 v11, v41, v41
	v_fmac_f32_e32 v11, v40, v40
	v_fmac_f32_e32 v11, v42, v42
	v_fmac_f32_e32 v11, v43, v43
	s_waitcnt lgkmcnt(5)
	v_fmac_f32_e32 v11, v36, v36
	v_fmac_f32_e32 v11, v37, v37
	v_fmac_f32_e32 v11, v38, v38
	v_fmac_f32_e32 v11, v39, v39
	s_waitcnt lgkmcnt(4)
	v_fmac_f32_e32 v11, v32, v32
	v_fmac_f32_e32 v11, v33, v33
	v_fmac_f32_e32 v11, v34, v34
	v_fmac_f32_e32 v11, v35, v35
	s_waitcnt lgkmcnt(3)
	v_fmac_f32_e32 v11, v28, v28
	v_fmac_f32_e32 v11, v29, v29
	v_fmac_f32_e32 v11, v30, v30
	v_fmac_f32_e32 v11, v31, v31
	s_waitcnt lgkmcnt(2)
	v_fmac_f32_e32 v11, v24, v24
	v_fmac_f32_e32 v11, v25, v25
	v_fmac_f32_e32 v11, v26, v26
	v_fmac_f32_e32 v11, v27, v27
	s_waitcnt lgkmcnt(1)
	v_fmac_f32_e32 v11, v20, v20
	v_fmac_f32_e32 v11, v21, v21
	v_fmac_f32_e32 v11, v22, v22
	v_fmac_f32_e32 v11, v23, v23
	s_waitcnt lgkmcnt(0)
	v_pk_mul_f32 v[8:9], v[12:13], v[12:13]
	v_lshlrev_b32_e32 v55, 16, v59
	v_add_f32_e32 v8, v11, v8
	v_add_f32_e32 v11, v8, v9
	v_pk_mul_f32 v[8:9], v[14:15], v[14:15]
	v_readlane_b32 s0, v251, 57
	v_add_f32_e32 v8, v11, v8
	v_add_f32_e32 v46, v8, v9
	ds_read_b128 v[8:11], v10 offset:18192
	v_readlane_b32 s1, v251, 58
	s_waitcnt lgkmcnt(0)
	v_pk_mul_f32 v[44:45], v[8:9], v[8:9]
	s_nop 0
	v_add_f32_e32 v44, v46, v44
	v_add_f32_e32 v46, v44, v45
	v_pk_mul_f32 v[44:45], v[10:11], v[10:11]
	s_nop 0
	v_add_f32_e32 v44, v46, v44
	v_add_f32_e32 v44, v44, v45
	ds_bpermute_b32 v45, v101, v44
	s_waitcnt lgkmcnt(0)
	v_add_f32_e32 v44, v44, v45
	ds_bpermute_b32 v45, v102, v44
	s_waitcnt lgkmcnt(0)
	v_add_f32_e32 v44, v44, v45
	ds_bpermute_b32 v45, v103, v44
	s_waitcnt lgkmcnt(0)
	v_add_f32_e32 v44, v44, v45
	v_fmamk_f32 v44, v44, 0x3b800000, v182
	v_cmp_gt_f32_e32 vcc, s56, v44
	v_mul_f32_e32 v45, 0x4b800000, v44
	s_nop 0
	v_cndmask_b32_e32 v44, v44, v45, vcc
	v_rsq_f32_e32 v44, v44
	s_nop 0
	v_mul_f32_e32 v45, 0x45800000, v44
	v_cndmask_b32_e32 v52, v44, v45, vcc
	v_mul_f32_e32 v38, v38, v52
	v_mul_f32_e32 v40, v40, v52
	v_mul_f32_e32 v36, v36, v52
	v_mul_f32_e32 v37, v37, v52
	v_mul_f32_e32 v41, v41, v52
	v_mul_f32_e32 v42, v42, v52
	v_mul_f32_e32 v43, v43, v52
	v_mul_f32_e32 v28, v28, v52
	v_mul_f32_e32 v32, v32, v52
	v_mul_f32_e32 v33, v33, v52
	v_mul_f32_e32 v34, v34, v52
	v_mul_f32_e32 v35, v35, v52
	v_mul_f32_e32 v20, v20, v52
	v_mul_f32_e32 v24, v24, v52
	v_mul_f32_e32 v8, v8, v52
	v_mul_f32_e32 v12, v12, v52
	s_waitcnt vmcnt(0)
	v_mul_f32_e32 v38, v206, v38
	v_mul_f32_e32 v40, v208, v40
	v_mul_f32_e32 v36, v204, v36
	v_mul_f32_e32 v37, v205, v37
	v_mul_f32_e32 v44, v38, v55
	v_mul_f32_e32 v38, v39, v52
	v_mul_f32_e32 v40, v40, v66
	v_mul_f32_e32 v41, v209, v41
	v_mul_f32_e32 v36, v36, v57
	v_mul_f32_e32 v37, v37, v56
	v_mul_f32_e32 v38, v207, v38
	v_mul_f32_e32 v41, v41, v65
	v_mul_f32_e32 v45, v38, v54
	v_cvt_pk_bf16_f32 v38, v40, v41
	v_cvt_pk_bf16_f32 v40, v36, v37
	v_lshl_add_u64 v[36:37], s[0:1], 0, v[60:61]
	v_mul_f32_e32 v42, v210, v42
	v_mul_f32_e32 v43, v211, v43
	v_lshl_add_u64 v[36:37], v[36:37], 0, v[156:157]
	v_mul_f32_e32 v42, v42, v64
	v_mul_f32_e32 v43, v43, v63
	v_cvt_pk_bf16_f32 v39, v42, v43
	v_cvt_pk_bf16_f32 v41, v44, v45
	global_store_dwordx4 v[36:37], v[38:41], off
	v_lshlrev_b32_e32 v42, 16, v16
	v_and_b32_e32 v43, 0xffff0000, v16
	v_lshlrev_b32_e32 v44, 16, v17
	v_and_b32_e32 v45, 0xffff0000, v17
	v_lshlrev_b32_e32 v46, 16, v18
	v_and_b32_e32 v47, 0xffff0000, v18
	v_lshlrev_b32_e32 v48, 16, v19
	v_and_b32_e32 v49, 0xffff0000, v19
	v_mul_f32_e32 v16, v28, v212
	v_mul_f32_e32 v28, v16, v46
	v_mul_f32_e32 v16, v29, v52
	v_mul_f32_e32 v16, v16, v213
	v_mul_f32_e32 v29, v16, v47
	v_mul_f32_e32 v16, v30, v52
	v_mul_f32_e32 v16, v16, v214
	v_mul_f32_e32 v30, v16, v48
	v_mul_f32_e32 v16, v31, v52
	v_mul_f32_e32 v16, v16, v215
	v_mul_f32_e32 v32, v32, v216
	v_mul_f32_e32 v33, v33, v217
	v_mul_f32_e32 v34, v34, v218
	v_mul_f32_e32 v35, v35, v219
	v_mul_f32_e32 v19, v16, v49
	v_mul_f32_e32 v32, v32, v42
	v_mul_f32_e32 v33, v33, v43
	v_mul_f32_e32 v34, v34, v44
	v_mul_f32_e32 v35, v35, v45
	v_cvt_pk_bf16_f32 v16, v32, v33
	v_cvt_pk_bf16_f32 v17, v34, v35
	v_cvt_pk_bf16_f32 v18, v28, v29
	v_cvt_pk_bf16_f32 v19, v30, v19
	global_store_dwordx4 v[36:37], v[16:19], off offset:128
	v_lshlrev_b32_e32 v28, 16, v4
	v_and_b32_e32 v29, 0xffff0000, v4
	v_lshlrev_b32_e32 v30, 16, v5
	v_and_b32_e32 v31, 0xffff0000, v5
	v_lshlrev_b32_e32 v32, 16, v6
	v_and_b32_e32 v33, 0xffff0000, v6
	v_lshlrev_b32_e32 v34, 16, v7
	v_and_b32_e32 v35, 0xffff0000, v7
	v_mul_f32_e32 v4, v20, v220
	v_mul_f32_e32 v20, v4, v32
	v_mul_f32_e32 v4, v21, v52
	v_mul_f32_e32 v4, v4, v221
	v_mul_f32_e32 v21, v4, v33
	v_mul_f32_e32 v4, v22, v52
	v_mul_f32_e32 v16, v24, v224
	v_mul_f32_e32 v24, v25, v52
	v_mul_f32_e32 v4, v4, v222
	v_mul_f32_e32 v17, v24, v225
	v_mul_f32_e32 v24, v26, v52
	v_mul_f32_e32 v22, v4, v34
	v_mul_f32_e32 v4, v23, v52
	v_mul_f32_e32 v18, v24, v226
	v_mul_f32_e32 v24, v27, v52
	v_mul_f32_e32 v4, v4, v223
	v_mul_f32_e32 v19, v24, v227
	v_mul_f32_e32 v7, v4, v35
	v_mul_f32_e32 v16, v16, v28
	v_mul_f32_e32 v17, v17, v29
	v_mul_f32_e32 v18, v18, v30
	v_mul_f32_e32 v19, v19, v31
	v_cvt_pk_bf16_f32 v4, v16, v17
	v_cvt_pk_bf16_f32 v5, v18, v19
	v_cvt_pk_bf16_f32 v6, v20, v21
	v_cvt_pk_bf16_f32 v7, v22, v7
	global_store_dwordx4 v[36:37], v[4:7], off offset:256
	v_lshlrev_b32_e32 v16, 16, v0
	v_and_b32_e32 v17, 0xffff0000, v0
	v_lshlrev_b32_e32 v18, 16, v1
	v_and_b32_e32 v19, 0xffff0000, v1
	v_lshlrev_b32_e32 v20, 16, v2
	v_and_b32_e32 v21, 0xffff0000, v2
	v_lshlrev_b32_e32 v22, 16, v3
	v_and_b32_e32 v23, 0xffff0000, v3
	v_mul_f32_e32 v0, v8, v228
	v_mul_f32_e32 v8, v0, v20
	v_mul_f32_e32 v0, v9, v52
	v_mul_f32_e32 v0, v0, v229
	v_mul_f32_e32 v9, v0, v21
	v_mul_f32_e32 v0, v10, v52
	v_mul_f32_e32 v4, v12, v232
	v_mul_f32_e32 v12, v13, v52
	v_mul_f32_e32 v0, v0, v230
	v_mul_f32_e32 v5, v12, v233
	v_mul_f32_e32 v12, v14, v52
	v_mul_f32_e32 v10, v0, v22
	v_mul_f32_e32 v0, v11, v52
	v_mul_f32_e32 v6, v12, v234
	v_mul_f32_e32 v12, v15, v52
	v_mul_f32_e32 v0, v0, v231
	v_mul_f32_e32 v7, v12, v235
	v_mul_f32_e32 v3, v0, v23
	v_mul_f32_e32 v4, v4, v16
	v_mul_f32_e32 v5, v5, v17
	v_mul_f32_e32 v6, v6, v18
	v_mul_f32_e32 v7, v7, v19
	v_cvt_pk_bf16_f32 v0, v4, v5
	v_cvt_pk_bf16_f32 v1, v6, v7
	v_cvt_pk_bf16_f32 v2, v8, v9
	v_cvt_pk_bf16_f32 v3, v10, v3
	global_store_dwordx4 v[36:37], v[0:3], off offset:384
	s_barrier

.LBB0_199:
	s_cmpk_gt_i32 s16, 0x3ff
	s_mov_b64 s[0:1], -1
	s_cbranch_scc0 .LBB0_221
	s_add_i32 s8, s16, 0xfffffc00
	s_and_b32 s9, s16, 3
	s_bfe_i32 s12, s16, 0x10008
	v_mov_b32_e32 v176, v167
	s_lshr_b32 s11, s8, 2
	s_and_b32 s12, s12, 3
	s_lshl_b32 s17, s9, 9
	v_readfirstlane_b32 s20, v176
	v_ashrrev_i32_e32 v169, 3, v176
	s_xor_b32 s13, s12, s11
	s_ashr_i32 s11, s20, 6
	s_lshr_b32 s19, s8, 4
	s_lshl_b32 s8, s9, 3
	v_add_u32_e32 v10, s17, v169
	v_mov_b64_e32 v[8:9], s[82:83]
	s_add_i32 s34, s11, s8
	v_lshlrev_b32_e32 v0, 3, v176
	s_lshl_b32 s12, s9, 7
	s_lshl_b32 s28, s9, 8
	v_mad_i64_i32 v[8:9], s[8:9], v10, s37, v[8:9]
	v_and_b32_e32 v166, 56, v0
	s_lshl_b32 s8, s19, 9
	s_mov_b32 s9, s29
	v_lshl_add_u64 v[8:9], v[8:9], 0, s[8:9]
	v_lshlrev_b32_e32 v10, 1, v166
	v_mov_b32_e32 v11, v157
	v_lshl_add_u64 v[32:33], v[8:9], 0, v[10:11]
	s_mov_b32 s8, 0x102000
	v_add_co_u32_e32 v12, vcc, s8, v32
	s_mov_b32 s8, 0x204000
	s_nop 0
	v_addc_co_u32_e32 v13, vcc, 0, v33, vcc
	v_add_co_u32_e32 v16, vcc, s8, v32
	s_mov_b32 s8, 0x306000
	s_nop 0
	v_addc_co_u32_e32 v17, vcc, 0, v33, vcc
	v_add_co_u32_e32 v20, vcc, s8, v32
	s_mov_b32 s8, 0x408000
	s_nop 0
	v_addc_co_u32_e32 v21, vcc, 0, v33, vcc
	v_add_co_u32_e32 v24, vcc, s8, v32
	s_mov_b32 s8, 0x50a000
	s_nop 0
	v_addc_co_u32_e32 v25, vcc, 0, v33, vcc
	v_add_co_u32_e32 v28, vcc, s8, v32
	s_mov_b32 s8, 0x60c000
	s_nop 0
	v_addc_co_u32_e32 v29, vcc, 0, v33, vcc
	v_add_co_u32_e32 v34, vcc, s8, v32
	s_mov_b32 s8, 0x70e000
	s_nop 0
	v_addc_co_u32_e32 v35, vcc, 0, v33, vcc
	v_add_co_u32_e32 v36, vcc, s8, v32
	s_lshl_b32 s8, s34, 5
	s_add_i32 s8, s8, s19
	s_lshl_b32 s0, s14, 4
	s_and_b32 s10, s15, 3
	s_ashr_i32 s9, s8, 31
	s_and_b32 s0, s0, 0xffffff00
	s_lshl_b32 s1, s10, 16
	s_and_b32 s18, s13, 3
	s_lshl_b64 s[8:9], s[8:9], 14
	v_readlane_b32 s24, v251, 49
	v_and_b32_e32 v171, 15, v176
	v_readlane_b32 s25, v251, 50
	s_add_u32 s8, s24, s8
	v_ashrrev_i32_e32 v177, 4, v176
	s_addc_u32 s9, s25, s9
	v_lshlrev_b32_e32 v40, 8, v171
	v_mov_b32_e32 v41, v157
	v_and_b32_e32 v168, 0x78, v0
	v_lshl_add_u32 v0, s19, 8, v177
	v_lshl_add_u64 v[40:41], s[8:9], 0, v[40:41]
	v_and_b32_e32 v80, 48, v176
	v_mov_b32_e32 v81, v157
	s_lshl_b32 s19, s13, 6
	v_addc_co_u32_e32 v37, vcc, 0, v33, vcc
	v_lshl_add_u64 v[40:41], v[40:41], 0, v[80:81]
	s_movk_i32 s8, 0x2000
	v_add_u32_e32 v42, s19, v177
	s_waitcnt lgkmcnt(0)
	v_ashrrev_i32_e32 v1, 31, v0
	v_add_co_u32_e32 v60, vcc, s8, v40
	v_ashrrev_i32_e32 v43, 31, v42
	v_lshlrev_b64 v[2:3], 10, v[0:1]
	v_add_u32_e32 v0, 32, v0
	v_addc_co_u32_e32 v61, vcc, 0, v41, vcc
	s_movk_i32 s8, 0x3000
	v_lshlrev_b64 v[52:53], 10, v[42:43]
	v_add_u32_e32 v42, 32, v42
	v_readlane_b32 s22, v251, 30
	v_ashrrev_i32_e32 v1, 31, v0
	v_add_co_u32_e32 v86, vcc, s8, v40
	v_readlane_b32 s8, v251, 28
	v_ashrrev_i32_e32 v43, 31, v42
	v_readlane_b32 s23, v251, 31
	v_lshlrev_b64 v[0:1], 10, v[0:1]
	v_readlane_b32 s9, v251, 29
	v_lshlrev_b64 v[42:43], 10, v[42:43]
	v_lshl_add_u64 v[2:3], s[22:23], 0, v[2:3]
	v_lshl_add_u64 v[0:1], s[22:23], 0, v[0:1]
	v_addc_co_u32_e32 v87, vcc, 0, v41, vcc
	v_lshl_add_u64 v[52:53], s[8:9], 0, v[52:53]
	v_lshl_add_u64 v[42:43], s[8:9], 0, v[42:43]
	s_movk_i32 s8, 0x1000
	v_lshl_add_u64 v[2:3], v[2:3], 0, s[28:29]
	v_lshlrev_b32_e32 v156, 1, v168
	v_lshl_add_u64 v[0:1], v[0:1], 0, s[28:29]
	v_lshl_add_u64 v[52:53], v[52:53], 0, s[28:29]
	v_lshl_add_u64 v[42:43], v[42:43], 0, s[28:29]
	v_add_co_u32_e32 v62, vcc, s8, v40
	v_lshl_add_u64 v[2:3], v[2:3], 0, v[156:157]
	v_lshl_add_u64 v[4:5], v[0:1], 0, v[156:157]
	v_lshl_add_u64 v[52:53], v[52:53], 0, v[156:157]
	v_lshl_add_u64 v[42:43], v[42:43], 0, v[156:157]
	v_addc_co_u32_e32 v63, vcc, 0, v41, vcc
	global_load_dwordx4 v[0:3], v[2:3], off
	s_nop 0
	global_load_dwordx4 v[4:7], v[4:5], off
	s_nop 0
	global_load_dwordx4 v[8:11], v[32:33], off
	s_nop 0
	global_load_dwordx4 v[12:15], v[12:13], off
	s_nop 0
	global_load_dwordx4 v[16:19], v[16:17], off
	s_nop 0
	global_load_dwordx4 v[20:23], v[20:21], off
	s_nop 0
	global_load_dwordx4 v[24:27], v[24:25], off
	s_nop 0
	global_load_dwordx4 v[28:31], v[28:29], off
	s_nop 0
	global_load_dwordx4 v[32:35], v[34:35], off
	s_nop 0
	global_load_dwordx4 v[36:39], v[36:37], off
	s_nop 0
	global_load_dwordx4 v[64:67], v[40:41], off
	global_load_dwordx4 v[48:51], v[40:41], off offset:64
	global_load_dwordx4 v[44:47], v[40:41], off offset:128
	global_load_dwordx4 v[88:91], v[40:41], off offset:192
	global_load_dwordx4 v[100:103], v[86:87], off offset:192
	global_load_dwordx4 v[82:85], v[52:53], off
	global_load_dwordx4 v[68:71], v[60:61], off offset:-4096
	global_load_dwordx4 v[116:119], v[42:43], off
	global_load_dwordx4 v[56:59], v[62:63], off offset:64
	s_nop 0
	global_load_dwordx4 v[40:43], v[62:63], off offset:128
	global_load_dwordx4 v[72:75], v[60:61], off
	global_load_dwordx4 v[52:55], v[60:61], off offset:64
	global_load_dwordx4 v[112:115], v[60:61], off offset:128
	global_load_dwordx4 v[94:97], v[60:61], off offset:192
	global_load_dwordx4 v[104:107], v[62:63], off offset:192
	global_load_dwordx4 v[76:79], v[86:87], off
	s_nop 0
	global_load_dwordx4 v[60:63], v[86:87], off offset:64
	global_load_dwordx4 v[108:111], v[86:87], off offset:128
	s_lshl_b32 s9, s11, 10
	s_add_i32 s21, s9, 16
	s_lshl_b32 s9, s11, 13
	s_movk_i32 s24, 0x110
	s_add_i32 s1, s1, s9
	v_mul_lo_u32 v81, v177, s24
	s_add_i32 s1, s1, s0
	v_and_b32_e32 v86, 63, v176
	v_bfe_u32 v172, v176, 4, 2
	v_add3_u32 v174, 16, v81, v156
	s_add_i32 s13, s21, 0x4400
	s_add_i32 s1, s1, 0x80000
	v_lshlrev_b32_e32 v173, 3, v172
	s_waitcnt vmcnt(0)
	ds_write_b128 v174, v[82:85] offset:33792
	ds_write_b128 v174, v[116:119] offset:42496
	s_add_i32 s8, s18, 1
	v_lshl_add_u32 v81, v86, 2, s13
	v_or_b32_e32 v82, s1, v86

.LBB0_221:
	s_and_b64 vcc, exec, s[0:1]
	s_cbranch_vccz .LBB0_198
	s_ashr_i32 s0, s16, 3
	s_bfe_u32 s1, s16, 0x20008
	s_xor_b32 s19, s1, s0
	s_lshr_b32 s0, s0, 30
	s_and_b32 s13, s16, 7
	v_mov_b32_e32 v97, v167
	s_add_i32 s0, s19, s0
	s_ashr_i32 s17, s0, 2
	v_ashrrev_i32_e32 v94, 3, v97
	s_lshl_b32 s34, s13, 8
	s_and_b32 s0, s0, -4
	s_lshl_b32 s8, s17, 8
	v_add_u32_e32 v22, s34, v94
	v_mov_b64_e32 v[16:17], s[78:79]
	s_sub_i32 s18, s19, s0
	v_mad_i64_i32 v[72:73], s[0:1], v22, s37, v[16:17]
	s_ashr_i32 s9, s8, 31
	v_add_u32_e32 v10, 64, v22
	v_add_u32_e32 v20, 0x80, v22
	v_add_u32_e32 v22, 0xc0, v22
	s_lshl_b64 s[0:1], s[8:9], 1
	v_mad_i64_i32 v[74:75], s[10:11], v10, s37, v[16:17]
	v_mad_i64_i32 v[78:79], s[10:11], v20, s37, v[16:17]
	v_mad_i64_i32 v[84:85], s[10:11], v22, s37, v[16:17]
	v_lshl_add_u64 v[8:9], v[72:73], 0, s[0:1]
	v_lshl_add_u64 v[10:11], v[74:75], 0, s[0:1]
	v_lshl_add_u64 v[20:21], v[78:79], 0, s[0:1]
	v_lshl_add_u64 v[16:17], v[84:85], 0, s[0:1]
	s_lshl_b32 s0, s13, 5
	s_add_i32 s0, s17, s0
	s_ashr_i32 s1, s0, 31
	v_ashrrev_i32_e32 v98, 4, v97
	v_lshlrev_b32_e32 v0, 3, v97
	s_lshl_b64 s[10:11], s[0:1], 16
	v_readfirstlane_b32 s12, v97
	v_and_b32_e32 v4, 0x78, v0
	v_add_u32_e32 v0, s8, v98
	s_add_u32 s10, s76, s10
	s_waitcnt lgkmcnt(0)
	v_ashrrev_i32_e32 v1, 31, v0
	s_addc_u32 s11, s77, s11
	s_ashr_i32 s9, s12, 1
	v_and_b32_e32 v96, 15, v97
	v_lshlrev_b64 v[2:3], 11, v[0:1]
	v_add_u32_e32 v0, 32, v0
	s_and_b32 s17, s9, 0xffffffe0
	v_ashrrev_i32_e32 v1, 31, v0
	v_or_b32_e32 v76, s17, v96
	v_lshlrev_b64 v[0:1], 11, v[0:1]
	v_ashrrev_i32_e32 v77, 31, v76
	v_bfe_u32 v95, v97, 4, 2
	v_and_b32_e32 v64, 7, v97
	v_lshl_add_u64 v[2:3], s[62:63], 0, v[2:3]
	s_mov_b32 s35, s29
	v_lshl_add_u64 v[0:1], s[62:63], 0, v[0:1]
	v_lshlrev_b64 v[24:25], 8, v[76:77]
	v_lshl_add_u64 v[2:3], v[2:3], 0, s[34:35]
	v_lshlrev_b32_e32 v156, 1, v4
	v_lshl_add_u64 v[0:1], v[0:1], 0, s[34:35]
	v_lshlrev_b32_e32 v18, 4, v64
	v_mov_b32_e32 v19, v157
	v_lshl_add_u64 v[24:25], s[10:11], 0, v[24:25]
	v_lshlrev_b32_e32 v26, 4, v95
	v_mov_b32_e32 v27, v157
	v_lshl_add_u64 v[2:3], v[2:3], 0, v[156:157]
	v_lshl_add_u64 v[4:5], v[0:1], 0, v[156:157]
	v_lshl_add_u64 v[8:9], v[8:9], 0, v[18:19]
	v_lshl_add_u64 v[12:13], v[10:11], 0, v[18:19]
	v_lshl_add_u64 v[20:21], v[20:21], 0, v[18:19]
	v_lshl_add_u64 v[22:23], v[16:17], 0, v[18:19]
	v_lshl_add_u64 v[28:29], v[24:25], 0, v[26:27]
	s_movk_i32 s1, 0x1000
	s_add_i32 s10, s0, 0x8200
	global_load_dwordx4 v[0:3], v[2:3], off
	s_nop 0
	global_load_dwordx4 v[4:7], v[4:5], off
	s_nop 0
	global_load_dwordx4 v[8:11], v[8:9], off
	s_nop 0
	global_load_dwordx4 v[12:15], v[12:13], off
	s_nop 0
	global_load_dwordx4 v[16:19], v[20:21], off
	s_nop 0
	global_load_dwordx4 v[20:23], v[22:23], off
	s_nop 0
	global_load_dwordx4 v[48:51], v[28:29], off
	global_load_dwordx4 v[40:43], v[28:29], off offset:64
	global_load_dwordx4 v[32:35], v[28:29], off offset:128
	global_load_dwordx4 v[24:27], v[28:29], off offset:192
	v_add_co_u32_e32 v28, vcc, s1, v28
	s_ashr_i32 s11, s10, 31
	s_nop 0
	v_addc_co_u32_e32 v29, vcc, 0, v29, vcc
	s_lshl_b64 s[10:11], s[10:11], 2
	global_load_dwordx4 v[52:55], v[28:29], off
	global_load_dwordx4 v[44:47], v[28:29], off offset:64
	global_load_dwordx4 v[36:39], v[28:29], off offset:128
	s_nop 0
	global_load_dwordx4 v[28:31], v[28:29], off offset:192
	s_add_u32 s10, s70, s10
	s_addc_u32 s11, s71, s11
	global_load_dword v100, v157, s[10:11]
	s_lshl_b32 s1, s18, 6
	s_add_i32 s1, s1, 64
	v_cmp_gt_i32_e32 vcc, s1, v97
	v_lshl_add_u32 v99, v97, 2, 16
	s_and_saveexec_b64 s[10:11], vcc
	s_cbranch_execz .LBB0_224
	s_lshl_b32 s1, s13, 13
	s_add_i32 s1, s8, s1
	s_add_i32 s1, s1, 0x10000
	v_add_u32_e32 v56, s1, v97
	v_ashrrev_i32_e32 v57, 31, v56
	v_lshl_add_u64 v[56:57], v[56:57], 2, s[26:27]
	global_load_dword v56, v[56:57], off
	v_add_u32_e32 v57, 0x23400, v99
	s_waitcnt vmcnt(0)
	ds_write_b32 v57, v56

.LBB0_253:
	v_readlane_b32 s86, v254, 22
	v_readlane_b32 s87, v254, 23
	v_readlane_b32 s0, v251, 53
	v_or_b32_e32 v62, s34, v104
	v_lshlrev_b64 v[60:61], 12, v[80:81]
	v_readlane_b32 s1, v251, 54
	v_lshlrev_b32_e32 v156, 1, v62
	v_cmp_gt_i32_e32 vcc, 64, v97
	s_waitcnt vmcnt(5)
	v_lshl_add_u64 v[0:1], s[0:1], 0, v[60:61]
	v_lshl_add_u64 v[0:1], v[0:1], 0, v[156:157]
	global_load_dwordx4 v[56:59], v[0:1], off
	global_load_dwordx4 v[16:19], v[0:1], off offset:128
	global_load_dwordx4 v[4:7], v[0:1], off offset:256
	s_nop 0
	global_load_dwordx4 v[0:3], v[0:1], off offset:384
	v_lshlrev_b32_e32 v236, 2, v62
	global_load_dwordx4 v[204:207], v236, s[86:87] offset:16
	global_load_dwordx4 v[208:211], v236, s[86:87]
	global_load_dwordx4 v[212:215], v236, s[86:87] offset:272
	global_load_dwordx4 v[216:219], v236, s[86:87] offset:256
	global_load_dwordx4 v[220:223], v236, s[86:87] offset:528
	global_load_dwordx4 v[224:227], v236, s[86:87] offset:512
	global_load_dwordx4 v[228:231], v236, s[86:87] offset:784
	global_load_dwordx4 v[232:235], v236, s[86:87] offset:768
	s_and_saveexec_b64 s[0:1], vcc
	s_cbranch_execz .LBB0_197
	s_waitcnt vmcnt(15)
	v_add_u32_e32 v8, 0x23800, v99
	ds_read_b32 v8, v8
	v_add_u32_e32 v9, 0x23b00, v99
	v_add_u32_e32 v10, 0x23900, v99
	ds_read_b32 v10, v10
	ds_read_b32 v9, v9
	s_waitcnt lgkmcnt(2)
	v_sub_f32_e32 v8, v100, v8
	v_mul_f32_e32 v8, 0x3fb8aa3b, v8
	v_exp_f32_e32 v8, v8
	s_waitcnt lgkmcnt(1)
	v_mul_f32_e32 v10, 0xbfb8aa3b, v10
	v_exp_f32_e32 v10, v10
	s_waitcnt lgkmcnt(0)
	v_fmac_f32_e32 v83, v9, v8
	v_max_f32_e64 v8, |v83|, v10
	v_div_scale_f32 v9, s[8:9], v8, v8, 1.0
	v_rcp_f32_e32 v10, v9
	v_div_scale_f32 v11, vcc, 1.0, v8, 1.0
	s_waitcnt vmcnt(14)
	v_fma_f32 v12, -v9, v10, 1.0
	v_fmac_f32_e32 v10, v12, v10
	v_mul_f32_e32 v12, v11, v10
	v_fma_f32 v13, -v9, v12, v11
	v_fmac_f32_e32 v12, v13, v10
	v_fma_f32 v9, -v9, v12, v11
	v_div_fmas_f32 v9, v9, v10, v12
	v_div_fixup_f32 v8, v9, v8, 1.0
	v_add_u32_e32 v9, 0x23a00, v99
	ds_write_b32 v9, v8
	s_branch .LBB0_197
